# early prep_late group = odd virtual block ids (stagger inside every XCD instead of between XCDs)
# speedup vs baseline: 1.0129x; 1.0021x over previous
.LBB0_83:
	v_writelane_b32 v250, s20, 2
	v_writelane_b32 v250, s17, 3
	v_writelane_b32 v250, s42, 4
	s_nop 1
	v_writelane_b32 v250, s43, 5
	v_writelane_b32 v250, s40, 6
	s_nop 1
	v_writelane_b32 v250, s41, 7
	s_or_b64 exec, exec, s[6:7]
	s_cmp_lt_i32 s86, 20
	s_cbranch_scc1 .Lpl_skip_early
	s_bitcmp1_b32 s86, 0
	s_cbranch_scc0 .Lpl_skip_early
	s_mov_b32 s100, 1
	s_branch .Lpl_entry

.LBB0_294:
	s_and_b64 vcc, exec, s[6:7]
	s_cbranch_vccz .LBB0_337
	s_cmp_lt_i32 s86, 20
	s_cbranch_scc1 .LBB0_337
	s_bitcmp1_b32 s86, 0
	s_cbranch_scc1 .LBB0_337
